# scan loop edge: next-step operand loads issued before the closing barrier of the step
# baseline (speedup 1.0000x reference)
; #define MFMA(a, b, c) __builtin_amdgcn_mfma_f32_16x16x32_bf16((a), (b), (c), 0, 0, 0)
; DI u16 f2bf(float x) { unsigned u = __float_as_uint(x); u += 0x7fffu + ((u >> 16) & 1u); return (u16)(u >> 16); }
; DI unsigned pack2(float a, float b) { return (unsigned)f2bf(a) | ((unsigned)f2bf(b) << 16); }
; DI float bflo(unsigned d) { return __uint_as_float(d << 16); }
; DI float bfhi(unsigned d) { return __uint_as_float(d & 0xffff0000u); }
; DI void scan_step(const Params& p, const ScanOps& ops, int n, int b, int h, int s, int j, int lane, f32x4& S0, f32x4& S1,
;                   bf16x8* sSb, u32x2* sUb) {
;   const int r = lane & 15, kg = lane >> 4;
;   bf16x8 sb[4];
; #pragma unroll
;   for (int ks = 0; ks < 4; ++ks) sb[ks] = sSb[ks * 64 + lane];
;   f32x4 u = (f32x4){bflo(ops.u0[0]), bfhi(ops.u0[0]), bflo(ops.u0[1]), bfhi(ops.u0[1])};
; #pragma unroll
;   for (int ks = 0; ks < 4; ++ks) u = MFMA(ops.nW[ks], sb[ks], u);
;   {
;     u32x2 t; t[0] = pack2(u[0], u[1]); t[1] = pack2(u[2], u[3]);
;     sUb[((j >> 1) * 64 + lane) * 2 + (j & 1)] = t;
;   }
;   __syncthreads();
;   bf16x8 ub[2];
; #pragma unroll
;   for (int k2 = 0; k2 < 2; ++k2) ub[k2] = *(const bf16x8*)&sUb[(k2 * 64 + lane) * 2];
;   f32x4 o = (f32x4){0.f, 0.f, 0.f, 0.f};
; #pragma unroll
;   for (int ks = 0; ks < 4; ++ks) o = MFMA(ops.qg[ks], sb[ks], o);
; #pragma unroll
;   for (int k2 = 0; k2 < 2; ++k2) o = MFMA(ops.aq[k2], ub[k2], o);
;   S0 = S0 * ops.dl; S1 = S1 * ops.dl;
; #pragma unroll
;   for (int k2 = 0; k2 < 2; ++k2) { S0 = MFMA(ops.kd[k2], ub[k2], S0); S1 = MFMA(ops.kd[2 + k2], ub[k2], S1); }
;   sSb[j * 64 + lane] = pack8(S0, S1);
; #pragma unroll
;   for (int jj = 0; jj < 4; ++jj) {
;     const size_t token = (size_t)b * SEQ + n * 64 + j * 16 + kg * 4 + jj;
;     G(p.odn)[token * 512 + h * 128 + s * 16 + r] = f2bf(o[jj]);
;   }
;   __syncthreads();
; }
.LBB0_622:
	ds_read_b128 v[206:209], v197
	ds_read_b128 v[210:213], v197 offset:1024
	ds_read_b128 v[128:131], v197 offset:2048
	ds_read_b128 v[124:127], v197 offset:3072
	s_waitcnt vmcnt(20)
	v_lshlrev_b32_e32 v214, 16, v168
	v_and_b32_e32 v215, 0xffff0000, v168
	v_lshlrev_b32_e32 v216, 16, v169
	v_and_b32_e32 v217, 0xffff0000, v169
	v_pk_mul_f32 v[102:103], v[102:103], v[164:165] op_sel_hi:[1,0]
	v_pk_mul_f32 v[100:101], v[100:101], v[164:165] op_sel_hi:[1,0]
	s_waitcnt lgkmcnt(3)
	v_mfma_f32_16x16x32_bf16 v[214:217], v[112:115], v[206:209], v[214:217]
	v_mul_f32_e64 v122, v122, v164
	v_mul_f32_e64 v123, v123, v164
	v_pk_mul_f32 v[120:121], v[120:121], v[164:165] op_sel_hi:[1,0]
	v_or_b32_e32 v112, 0x400, v8
	v_mfma_f32_16x16x32_bf16 v[206:209], v[116:119], v[206:209], 0
	v_mov_b32_e32 v113, v9
	v_or_b32_e32 v114, 0x800, v8
	v_mov_b32_e32 v115, v9
	s_waitcnt lgkmcnt(2)
	v_mfma_f32_16x16x32_bf16 v[214:217], v[104:107], v[210:213], v[214:217]
	v_or_b32_e32 v116, 0xc00, v8
	v_mov_b32_e32 v117, v9
	v_mfma_f32_16x16x32_bf16 v[108:111], v[108:111], v[210:213], v[206:209]
	s_waitcnt lgkmcnt(1)
	v_mfma_f32_16x16x32_bf16 v[96:99], v[96:99], v[128:131], v[214:217]
	s_add_i32 s25, s0, 2
	s_add_i32 s0, s0, 4
	s_min_u32 s0, s0, 0x7f
	v_mfma_f32_16x16x32_bf16 v[84:87], v[84:87], v[128:131], v[108:111]
	s_or_b32 s27, s0, s18
	s_min_u32 s26, s25, 0x7c
	s_mul_i32 s0, s27, 0x12000
	s_waitcnt lgkmcnt(0)
	v_mfma_f32_16x16x32_bf16 v[32:35], v[32:35], v[124:127], v[96:99]
	s_add_i32 s30, s22, s26
	s_add_i32 s26, s18, s26
	s_lshl_b32 s27, s27, 2
	v_mfma_f32_16x16x32_bf16 v[84:87], v[88:91], v[124:127], v[84:87]
	s_lshl_b32 s31, s26, 2
	s_nop 2
	v_bfe_u32 v88, v32, 16, 1
	v_bfe_u32 v90, v34, 16, 1
	v_bfe_u32 v89, v33, 16, 1
	v_bfe_u32 v91, v35, 16, 1
	v_add3_u32 v32, v32, v88, s24
	v_add3_u32 v34, v34, v90, s24
	v_add3_u32 v33, v33, v89, s24
	v_add3_u32 v35, v35, v91, s24
	v_lshrrev_b32_e32 v32, 16, v32
	v_lshrrev_b32_e32 v34, 16, v34
	v_and_or_b32 v32, v33, s23, v32
	v_and_or_b32 v33, v35, s23, v34
	ds_write_b64 v147, v[32:33] offset:4096
	s_waitcnt lgkmcnt(0)
	s_barrier
	ds_read_b128 v[32:35], v197 offset:4096
	ds_read_b128 v[88:91], v197 offset:5120
	s_waitcnt lgkmcnt(1)
	v_mfma_f32_16x16x32_bf16 v[16:19], v[16:19], v[32:35], v[100:103]
	v_or_b32_e32 v218, 0x400, v152
	v_mov_b32_e32 v219, v153
	v_or_b32_e32 v194, 0x800, v152
	v_mfma_f32_16x16x32_bf16 v[20:23], v[20:23], v[32:35], v[120:123]
	v_mov_b32_e32 v195, v153
	v_or_b32_e32 v128, 0xc00, v152
	v_mov_b32_e32 v129, v153
	v_mfma_f32_16x16x32_bf16 v[40:43], v[40:43], v[32:35], v[84:87]
	ds_read_b64 v[32:33], v149
	s_cmpk_lt_u32 s25, 0x7e
	s_waitcnt lgkmcnt(0)
	v_lshl_add_u64 v[34:35], v[32:33], 0, s[12:13]
	v_mfma_f32_16x16x32_bf16 v[100:103], v[4:7], v[88:91], v[16:19]
	v_lshl_add_u64 v[34:35], v[34:35], 0, s[14:15]
	v_lshl_add_u64 v[34:35], v[34:35], 0, v[156:157]
	v_lshl_add_u64 v[4:5], v[34:35], 0, v[112:113]
	v_mfma_f32_16x16x32_bf16 v[120:123], v[12:15], v[88:91], v[20:23]
	v_lshl_add_u64 v[6:7], v[34:35], 0, v[114:115]
	s_nop 2
	v_bfe_u32 v12, v100, 16, 1
	v_bfe_u32 v14, v102, 16, 1
	v_mfma_f32_16x16x32_bf16 v[0:3], v[0:3], v[88:91], v[40:43]
	v_lshl_add_u64 v[16:17], v[34:35], 0, v[116:117]
	v_bfe_u32 v18, v120, 16, 1
	v_bfe_u32 v20, v122, 16, 1
	v_bfe_u32 v13, v101, 16, 1
	v_bfe_u32 v15, v103, 16, 1
	v_bfe_u32 v19, v121, 16, 1
	v_bfe_u32 v21, v123, 16, 1
	s_nop 0
	v_bfe_u32 v22, v0, 16, 1
	v_bfe_u32 v23, v1, 16, 1
	v_bfe_u32 v34, v2, 16, 1
	v_bfe_u32 v35, v3, 16, 1
	v_add3_u32 v12, v100, v12, s24
	v_add3_u32 v14, v102, v14, s24
	v_add3_u32 v18, v120, v18, s24
	v_add3_u32 v20, v122, v20, s24
	v_lshl_add_u64 v[32:33], v[32:33], 0, v[154:155]
	v_add3_u32 v13, v101, v13, s24
	v_add3_u32 v15, v103, v15, s24
	v_add3_u32 v19, v121, v19, s24
	v_add3_u32 v21, v123, v21, s24
	v_add3_u32 v22, v0, v22, s24
	v_add3_u32 v23, v1, v23, s24
	v_add3_u32 v34, v2, v34, s24
	v_add3_u32 v35, v3, v35, s24
	v_lshrrev_b32_e32 v0, 16, v12
	v_lshrrev_b32_e32 v1, 16, v14
	v_lshrrev_b32_e32 v2, 16, v18
	v_lshrrev_b32_e32 v3, 16, v20
	v_lshl_add_u64 v[32:33], v[32:33], 0, v[8:9]
	v_and_or_b32 v0, v13, s23, v0
	v_and_or_b32 v1, v15, s23, v1
	v_and_or_b32 v2, v19, s23, v2
	v_and_or_b32 v3, v21, s23, v3
	ds_write_b128 v151, v[0:3]
	global_store_short_d16_hi v[32:33], v22, off
	global_store_short_d16_hi v[4:5], v23, off
	global_store_short_d16_hi v[6:7], v34, off
	global_store_short_d16_hi v[16:17], v35, off
	s_waitcnt lgkmcnt(0)
	s_barrier
; #define MFMA(a, b, c) __builtin_amdgcn_mfma_f32_16x16x32_bf16((a), (b), (c), 0, 0, 0)
; #define AS1 __attribute__((address_space(1)))
; DI unsigned pack2(float a, float b) { return (unsigned)f2bf(a) | ((unsigned)f2bf(b) << 16); }
; DI float bflo(unsigned d) { return __uint_as_float(d << 16); }
; DI float bfhi(unsigned d) { return __uint_as_float(d & 0xffff0000u); }
; DI void scan_load(const Params& p, int bh, int s, int n, int j, int lane, ScanOps& o) {
;   n = n > 127 ? 127 : n;
;   const char AS1* base = (const char AS1*)p.dnops + (size_t)(bh * 128 + n) * DN_ITEM;
;   gb8p negW = (gb8p)base;
;   gb8p qg = (gb8p)(base + 16384);
;   gb8p kdT = (gb8p)(base + 32768);
;   gb8p aqk = (gb8p)(base + 49152);
;   const u32x2 AS1* u0 = (const u32x2 AS1*)(base + 57344);
; #pragma unroll
;   for (int ks = 0; ks < 4; ++ks) o.nW[ks] = negW[(j * 4 + ks) * 64 + lane];
; #pragma unroll
;   for (int ks = 0; ks < 4; ++ks) o.qg[ks] = qg[(j * 4 + ks) * 64 + lane];
; #pragma unroll
;   for (int k2 = 0; k2 < 2; ++k2) o.aq[k2] = aqk[(j * 2 + k2) * 64 + lane];
; #pragma unroll
;   for (int mm = 0; mm < 2; ++mm)
; #pragma unroll
;     for (int k2 = 0; k2 < 2; ++k2) o.kd[mm * 2 + k2] = kdT[((2 * j + mm) * 2 + k2) * 64 + lane];
;   o.u0 = u0[(s * 4 + j) * 64 + lane];
;   o.dl = ((const float AS1*)p.dl)[bh * 128 + n];
; }
; DI void scan_step(const Params& p, const ScanOps& ops, int n, int b, int h, int s, int j, int lane, f32x4& S0, f32x4& S1,
;                   bf16x8* sSb, u32x2* sUb) {
;   const int r = lane & 15, kg = lane >> 4;
;   bf16x8 sb[4];
; #pragma unroll
;   for (int ks = 0; ks < 4; ++ks) sb[ks] = sSb[ks * 64 + lane];
;   f32x4 u = (f32x4){bflo(ops.u0[0]), bfhi(ops.u0[0]), bflo(ops.u0[1]), bfhi(ops.u0[1])};
; #pragma unroll
;   for (int ks = 0; ks < 4; ++ks) u = MFMA(ops.nW[ks], sb[ks], u);
;   {
;     u32x2 t; t[0] = pack2(u[0], u[1]); t[1] = pack2(u[2], u[3]);
;     sUb[((j >> 1) * 64 + lane) * 2 + (j & 1)] = t;
;   }
;   __syncthreads();
;   bf16x8 ub[2];
; #pragma unroll
;   for (int k2 = 0; k2 < 2; ++k2) ub[k2] = *(const bf16x8*)&sUb[(k2 * 64 + lane) * 2];
	ds_read_b128 v[0:3], v197
	ds_read_b64 v[20:21], v141
	ds_read_b64 v[22:23], v145
	ds_read_b128 v[4:7], v197 offset:1024
	ds_read_b128 v[12:15], v197 offset:2048
	ds_read_b128 v[124:127], v197 offset:3072
	s_waitcnt vmcnt(4)
	v_lshlrev_b32_e32 v104, 16, v166
	v_and_b32_e32 v105, 0xffff0000, v166
	v_lshlrev_b32_e32 v106, 16, v167
	v_and_b32_e32 v107, 0xffff0000, v167
	s_waitcnt lgkmcnt(0)
	s_nop 0
	v_mfma_f32_16x16x32_bf16 v[16:19], v[72:75], v[0:3], v[104:107]
	v_lshl_add_u64 v[20:21], v[20:21], 0, s[0:1]
	v_mov_b32_e32 v84, s27
	v_readfirstlane_b32 s26, v22
	v_mfma_f32_16x16x32_bf16 v[0:3], v[92:95], v[0:3], 0
	v_readfirstlane_b32 s27, v23
	v_lshl_add_u64 v[40:41], v[20:21], 0, s[8:9]
	v_lshl_add_u64 v[42:43], v[20:21], 0, v[158:159]
	v_mfma_f32_16x16x32_bf16 v[16:19], v[56:59], v[4:7], v[16:19]
	v_readfirstlane_b32 s28, v20
	v_readfirstlane_b32 s29, v21
	global_load_dword v164, v84, s[26:27]
	s_nop 3
	global_load_dwordx4 v[112:115], v198, s[28:29]
	global_load_dwordx4 v[104:107], v198, s[28:29] offset:1024
	global_load_dwordx4 v[96:99], v198, s[28:29] offset:2048
	global_load_dwordx4 v[32:35], v198, s[28:29] offset:3072
	v_mfma_f32_16x16x32_bf16 v[4:7], v[76:79], v[4:7], v[0:3]
	v_readfirstlane_b32 s26, v40
	v_add_co_u32_e32 v40, vcc, s19, v42
	v_mfma_f32_16x16x32_bf16 v[48:51], v[48:51], v[12:15], v[16:19]
	v_lshl_add_u64 v[22:23], v[20:21], 0, s[2:3]
	v_lshl_add_u64 v[20:21], v[20:21], 0, v[160:161]
	v_readfirstlane_b32 s27, v41
	v_mfma_f32_16x16x32_bf16 v[56:59], v[80:83], v[12:15], v[4:7]
	v_addc_co_u32_e32 v41, vcc, 0, v43, vcc
	v_readfirstlane_b32 s28, v22
	v_mfma_f32_16x16x32_bf16 v[28:31], v[28:31], v[124:127], v[48:51]
	v_readfirstlane_b32 s29, v23
	v_add_co_u32_e32 v74, vcc, s20, v20
	v_mfma_f32_16x16x32_bf16 v[48:51], v[68:71], v[124:127], v[56:59]
	v_lshl_add_u64 v[72:73], v[42:43], 0, s[10:11]
	v_addc_co_u32_e32 v75, vcc, 0, v21, vcc
	s_nop 2
	v_bfe_u32 v56, v28, 16, 1
	v_bfe_u32 v58, v30, 16, 1
	v_bfe_u32 v57, v29, 16, 1
	v_bfe_u32 v59, v31, 16, 1
	v_add3_u32 v28, v28, v56, s24
	v_add3_u32 v30, v30, v58, s24
	v_add3_u32 v29, v29, v57, s24
	v_add3_u32 v31, v31, v59, s24
	v_lshrrev_b32_e32 v28, 16, v28
	v_lshrrev_b32_e32 v30, 16, v30
	v_and_or_b32 v28, v29, s23, v28
	v_and_or_b32 v29, v31, s23, v30
	global_load_dwordx4 v[84:87], v202, s[26:27]
	global_load_dwordx4 v[88:91], v204, s[26:27]
	s_nop 0
	global_load_dwordx4 v[40:43], v[40:41], off
	s_nop 0
	global_load_dwordx4 v[0:3], v[72:73], off offset:1024
	global_load_dwordx4 v[16:19], v198, s[28:29]
	global_load_dwordx4 v[4:7], v198, s[28:29] offset:1024
	global_load_dwordx4 v[108:111], v201, s[26:27]
	global_load_dwordx4 v[20:23], v202, s[28:29]
	global_load_dwordx4 v[116:119], v198, s[26:27]
	global_load_dwordx4 v[12:15], v198, s[28:29] offset:3072
	global_load_dwordx2 v[168:169], v[74:75], off
	ds_write_b64 v147, v[28:29] offset:4096
	s_waitcnt lgkmcnt(0)
	s_barrier
; #define MFMA(a, b, c) __builtin_amdgcn_mfma_f32_16x16x32_bf16((a), (b), (c), 0, 0, 0)
; DI u16 f2bf(float x) { unsigned u = __float_as_uint(x); u += 0x7fffu + ((u >> 16) & 1u); return (u16)(u >> 16); }
; DI void scan_step(const Params& p, const ScanOps& ops, int n, int b, int h, int s, int j, int lane, f32x4& S0, f32x4& S1,
;                   bf16x8* sSb, u32x2* sUb) {
;     ...
;   f32x4 o = (f32x4){0.f, 0.f, 0.f, 0.f};
; #pragma unroll
;   for (int ks = 0; ks < 4; ++ks) o = MFMA(ops.qg[ks], sb[ks], o);
; #pragma unroll
;   for (int k2 = 0; k2 < 2; ++k2) o = MFMA(ops.aq[k2], ub[k2], o);
;   S0 = S0 * ops.dl; S1 = S1 * ops.dl;
; #pragma unroll
;   for (int k2 = 0; k2 < 2; ++k2) { S0 = MFMA(ops.kd[k2], ub[k2], S0); S1 = MFMA(ops.kd[2 + k2], ub[k2], S1); }
;   sSb[j * 64 + lane] = pack8(S0, S1);
; #pragma unroll
;   for (int jj = 0; jj < 4; ++jj) {
;     const size_t token = (size_t)b * SEQ + n * 64 + j * 16 + kg * 4 + jj;
;     G(p.odn)[token * 512 + h * 128 + s * 16 + r] = f2bf(o[jj]);
;   }
;   __syncthreads();
; }
; DI void dn_scan_block(const Params& p, int item, char* smem) {
;   const int lane = threadIdx.x & 63, j = threadIdx.x >> 6, r = lane & 15, kg = lane >> 4;
;   const int bh = item >> 3, s = item & 7, b = bh >> 2, h = bh & 3;
;   bf16x8* sSb = (bf16x8*)smem;
;   u32x2* sUb = (u32x2*)(smem + 4096);
;   f32x4 S0 = (f32x4){0.f, 0.f, 0.f, 0.f}, S1 = (f32x4){0.f, 0.f, 0.f, 0.f};
;   __syncthreads();
;   sSb[j * 64 + lane] = pack8(S0, S1);
;   ScanOps A, B;
;   scan_load(p, bh, s, 0, j, lane, A);
;   scan_load(p, bh, s, 1, j, lane, B);
;   __syncthreads();
; #pragma unroll 1
;   for (int n0 = 0; n0 < 128; n0 += 2) {
;     scan_step(p, A, n0, b, h, s, j, lane, S0, S1, sSb, sUb);
;     scan_load(p, bh, s, n0 + 2, j, lane, A);
;     scan_step(p, B, n0 + 1, b, h, s, j, lane, S0, S1, sSb, sUb);
;     scan_load(p, bh, s, n0 + 3, j, lane, B);
;   }
; #pragma unroll
;   for (int jj = 0; jj < 4; ++jj) {
;     p.out[O_PDELTA + ((size_t)bh * 128 + 32 * j + kg * 4 + jj) * 128 + s * 16 + r] = S0[jj];
;     p.out[O_PDELTA + ((size_t)bh * 128 + 32 * j + 16 + kg * 4 + jj) * 128 + s * 16 + r] = S1[jj];
;   }
	ds_read_b128 v[28:31], v197 offset:4096
	ds_read_b128 v[56:59], v197 offset:5120
	s_waitcnt lgkmcnt(0)
	v_mfma_f32_16x16x32_bf16 v[48:51], v[52:55], v[28:31], v[48:51]
	v_mul_f32_e64 v54, v162, v102
	v_mul_f32_e64 v55, v162, v103
	v_pk_mul_f32 v[52:53], v[162:163], v[100:101] op_sel_hi:[0,1]
	s_mul_i32 s0, s30, 0x12000
	v_mfma_f32_16x16x32_bf16 v[24:27], v[24:27], v[56:59], v[48:51]
	v_mov_b32_e32 v68, s31
	v_lshl_add_u64 v[8:9], v[8:9], 0, s[16:17]
	v_mfma_f32_16x16x32_bf16 v[52:55], v[60:63], v[28:31], v[52:55]
	v_mul_f32_e64 v62, v162, v122
	v_mul_f32_e64 v63, v162, v123
	v_pk_mul_f32 v[60:61], v[162:163], v[120:121] op_sel_hi:[0,1]
	v_mfma_f32_16x16x32_bf16 v[100:103], v[36:39], v[56:59], v[52:55]
	s_nop 0
	v_mfma_f32_16x16x32_bf16 v[28:31], v[64:67], v[28:31], v[60:63]
	s_nop 1
	v_bfe_u32 v52, v24, 16, 1
	v_bfe_u32 v53, v25, 16, 1
	v_bfe_u32 v54, v26, 16, 1
	ds_read_b64 v[60:61], v149
	v_mfma_f32_16x16x32_bf16 v[120:123], v[44:47], v[56:59], v[28:31]
	v_bfe_u32 v55, v27, 16, 1
	v_add3_u32 v52, v24, v52, s24
	v_add3_u32 v53, v25, v53, s24
	v_bfe_u32 v28, v100, 16, 1
	v_bfe_u32 v30, v102, 16, 1
	s_nop 2
	v_bfe_u32 v44, v120, 16, 1
	v_bfe_u32 v46, v122, 16, 1
	s_waitcnt lgkmcnt(0)
	v_lshl_add_u64 v[62:63], v[60:61], 0, s[12:13]
	v_bfe_u32 v29, v101, 16, 1
	v_bfe_u32 v31, v103, 16, 1
	v_bfe_u32 v45, v121, 16, 1
	v_bfe_u32 v47, v123, 16, 1
	v_add3_u32 v28, v100, v28, s24
	v_add3_u32 v30, v102, v30, s24
	v_add3_u32 v44, v120, v44, s24
	v_add3_u32 v46, v122, v46, s24
	v_lshl_add_u64 v[60:61], v[60:61], 0, v[154:155]
	v_lshl_add_u64 v[48:49], v[62:63], 0, s[14:15]
	v_add3_u32 v29, v101, v29, s24
	v_add3_u32 v31, v103, v31, s24
	v_add3_u32 v45, v121, v45, s24
	v_add3_u32 v47, v123, v47, s24
	v_add3_u32 v54, v26, v54, s24
	v_add3_u32 v55, v27, v55, s24
	v_lshrrev_b32_e32 v24, 16, v28
	v_lshrrev_b32_e32 v25, 16, v30
	v_lshrrev_b32_e32 v26, 16, v44
	v_lshrrev_b32_e32 v27, 16, v46
	v_lshl_add_u64 v[50:51], v[60:61], 0, v[152:153]
	v_lshl_add_u64 v[48:49], v[48:49], 0, v[156:157]
	v_and_or_b32 v24, v29, s23, v24
	v_and_or_b32 v25, v31, s23, v25
	v_and_or_b32 v26, v45, s23, v26
	v_and_or_b32 v27, v47, s23, v27
	v_lshl_add_u64 v[36:37], v[48:49], 0, v[218:219]
	v_lshl_add_u64 v[38:39], v[48:49], 0, v[194:195]
	v_lshl_add_u64 v[48:49], v[48:49], 0, v[128:129]
	ds_write_b128 v151, v[24:27]
	global_store_short_d16_hi v[50:51], v52, off
	global_store_short_d16_hi v[36:37], v53, off
	global_store_short_d16_hi v[38:39], v54, off
	global_store_short_d16_hi v[48:49], v55, off
	ds_read_b64 v[24:25], v141
	ds_read_b64 v[26:27], v145
	v_lshl_add_u64 v[152:153], v[152:153], 0, s[16:17]
	s_waitcnt lgkmcnt(0)
	v_lshl_add_u64 v[24:25], v[24:25], 0, s[0:1]
	v_readfirstlane_b32 s26, v26
	v_readfirstlane_b32 s27, v27
	v_lshl_add_u64 v[36:37], v[24:25], 0, s[8:9]
	v_lshl_add_u64 v[38:39], v[24:25], 0, v[158:159]
	v_readfirstlane_b32 s28, v24
	v_readfirstlane_b32 s29, v25
	s_nop 0
	global_load_dword v162, v68, s[26:27] offset:12
	s_nop 2
	global_load_dwordx4 v[72:75], v198, s[28:29]
	global_load_dwordx4 v[56:59], v198, s[28:29] offset:1024
	global_load_dwordx4 v[48:51], v198, s[28:29] offset:2048
	global_load_dwordx4 v[28:31], v198, s[28:29] offset:3072
	v_readfirstlane_b32 s26, v36
	v_readfirstlane_b32 s27, v37
	v_lshl_add_u64 v[36:37], v[38:39], 0, s[10:11]
	v_add_co_u32_e32 v38, vcc, s19, v38
	v_lshl_add_u64 v[26:27], v[24:25], 0, s[2:3]
	v_lshl_add_u64 v[24:25], v[24:25], 0, v[160:161]
	v_addc_co_u32_e32 v39, vcc, 0, v39, vcc
	v_add_co_u32_e32 v124, vcc, s20, v24
	v_readfirstlane_b32 s28, v26
	v_readfirstlane_b32 s29, v27
	v_addc_co_u32_e32 v125, vcc, 0, v25, vcc
	global_load_dwordx4 v[80:83], v202, s[26:27]
	global_load_dwordx4 v[68:71], v204, s[26:27]
	global_load_dwordx4 v[52:55], v[38:39], off
	global_load_dwordx4 v[24:27], v[36:37], off offset:1024
	global_load_dwordx4 v[60:63], v198, s[28:29]
	s_nop 0
	global_load_dwordx4 v[36:39], v198, s[28:29] offset:1024
	global_load_dwordx4 v[76:79], v201, s[26:27]
	global_load_dwordx4 v[64:67], v202, s[28:29]
	global_load_dwordx4 v[92:95], v198, s[26:27]
	global_load_dwordx4 v[44:47], v198, s[28:29] offset:3072
	global_load_dwordx2 v[166:167], v[124:125], off
	s_waitcnt lgkmcnt(0)
	s_barrier
	s_mov_b32 s0, s25
	s_cbranch_scc1 .LBB0_622
	s_waitcnt vmcnt(0)
	v_mov_b32_e32 v0, 0x100d8
	ds_read_b64 v[0:1], v0
	v_add_u32_e32 v2, s18, v178
	v_or_b32_e32 v2, v2, v200
	v_lshlrev_b32_e32 v2, 9, v2
	v_mov_b32_e32 v3, 0
	s_mov_b32 s1, 0
	s_waitcnt lgkmcnt(0)
	v_lshl_add_u64 v[0:1], v[0:1], 0, v[2:3]
	s_lshl_b32 s0, s21, 2
	v_mov_b32_e32 v151, v3
	v_lshl_add_u64 v[0:1], v[0:1], 0, s[0:1]
	v_lshl_add_u64 v[0:1], v[0:1], 0, v[150:151]
	v_add_co_u32_e32 v2, vcc, 0x8080000, v0
	s_nop 1
	v_addc_co_u32_e32 v3, vcc, 0, v1, vcc
	v_add_co_u32_e32 v0, vcc, 0x8082000, v0
	flat_store_dword v[2:3], v100
	s_nop 0
	v_addc_co_u32_e32 v1, vcc, 0, v1, vcc
	flat_store_dword v[0:1], v120
	flat_store_dword v[2:3], v101 offset:512
	flat_store_dword v[0:1], v121 offset:512
	flat_store_dword v[2:3], v102 offset:1024
	flat_store_dword v[0:1], v122 offset:1024
	flat_store_dword v[2:3], v103 offset:1536
	flat_store_dword v[0:1], v123 offset:1536
